# baseline (speedup 1.0000x reference)
; __device__ __forceinline__ u16 f2bf(float f) { return (u16)(pack2(f, f) & 0xffffu); }
; __device__ __forceinline__ float lo_bf(unsigned u) { return __uint_as_float(u << 16); }
; __device__ __forceinline__ float hi_bf(unsigned u) { return __uint_as_float(u & 0xffff0000u); }
; #define MFMA16(a, b, c) __builtin_amdgcn_mfma_f32_16x16x32_bf16(a, b, c, 0, 0, 0)
; __device__ __forceinline__ void scan_block(const Params& p, char* smem, int bs) {
;     ...
;   auto step = [&](const int ch, u32x4 (&F)[14], uint2& U) {
;     const int par = ch & 1;
;     const float cd = cdp[ch];
;     union { u32x4 u; bf16x8 v; } cv;
;     f32x4 aw = {0.f, 0.f, 0.f, 0.f}, aq = aw;
; #pragma unroll
;     for (int s2 = 0; s2 < 4; ++s2) {
;       union { u32x4 u; bf16x8 v; } sb;
;       sb.u = *(const u32x4*)(Sl + ((par * 4 + s2) * 64 + lane) * 16);
;       cv.u = F[s2];     aw = MFMA16(cv.v, sb.v, aw);
;       cv.u = F[4 + s2]; aq = MFMA16(cv.v, sb.v, aq);
;     }
;     f32x4 vn;
;     vn[0] = lo_bf(U.x) - aw[0]; vn[1] = hi_bf(U.x) - aw[1];
;     vn[2] = lo_bf(U.y) - aw[2]; vn[3] = hi_bf(U.y) - aw[3];
;     {
;       uint2 pk; pk.x = pack2(vn[0], vn[1]); pk.y = pack2(vn[2], vn[3]);
;       *(uint2*)(Vl + ((par * 2 + (w >> 1)) * 64 + lane) * 16 + (w & 1) * 8) = pk;
;     }
;     __syncthreads();
;     bf16x8 Vb[2];
; #pragma unroll
;     for (int m = 0; m < 2; ++m) { cv.u = *(const u32x4*)(Vl + ((par * 2 + m) * 64 + lane) * 16); Vb[m] = cv.v; }
;     cv.u = F[8]; aq = MFMA16(cv.v, Vb[0], aq);
;     if (w >= 2) { cv.u = F[9]; aq = MFMA16(cv.v, Vb[1], aq); }
;     f32x4 n0 = S0 * cd, n1 = S1 * cd;
;     cv.u = F[10]; n0 = MFMA16(cv.v, Vb[0], n0);
;     cv.u = F[11]; n0 = MFMA16(cv.v, Vb[1], n0);
;     cv.u = F[12]; n1 = MFMA16(cv.v, Vb[0], n1);
;     cv.u = F[13]; n1 = MFMA16(cv.v, Vb[1], n1);
;     S0 = n0; S1 = n1;
;     {
;       cv.v = pack8(S0, S1);
;       *(u32x4*)(Sl + (((par ^ 1) * 4 + w) * 64 + lane) * 16) = cv.u;
;     }
;     {
;       const int nx = (ch + 3 < 256) ? ch + 3 : 255;
;       LOADSET(F, U, nx);
;     }
; #pragma unroll
;     for (int jj = 0; jj < 4; ++jj) {
;       const size_t row = (size_t)b * T + ch * 64 + w * 16 + 4 * fq + jj;
;       oraw[row * 1024 + hh * 128 + slice * 16 + fr] = f2bf(aq[jj]);
;     }
;     __syncthreads();
;   };
.LBB0_874:
	s_waitcnt vmcnt(40)
	s_add_i32 s63, s61, 3
	s_and_b32 s0, s63, 1
	s_add_u32 s48, s54, s18
	s_addc_u32 s49, s55, s19
	s_add_u32 s98, s54, s18
	s_addc_u32 s99, s55, s19
	s_lshl_b32 s65, s0, 12
	v_or_b32_e32 v210, s65, v215
	ds_read_b128 v[176:179], v210
	ds_read_b128 v[180:183], v210 offset:1024
	ds_read_b128 v[246:249], v210 offset:2048
	ds_read_b128 v[234:237], v210 offset:3072
	s_lshl_b32 s64, s0, 11
	v_add_u32_e32 v226, s64, v223
	s_waitcnt lgkmcnt(3)
	v_mfma_f32_16x16x32_bf16 v[52:55], v[52:55], v[176:179], 0
	s_waitcnt lgkmcnt(2)
	v_mfma_f32_16x16x32_bf16 v[48:51], v[48:51], v[180:183], v[52:55]
	s_waitcnt lgkmcnt(1)
	v_mfma_f32_16x16x32_bf16 v[46:49], v[44:47], v[246:249], v[48:51]
	v_lshlrev_b32_e32 v45, 16, v194
	v_mfma_f32_16x16x32_bf16 v[36:39], v[36:39], v[176:179], 0
	s_waitcnt lgkmcnt(0)
	v_mfma_f32_16x16x32_bf16 v[40:43], v[40:43], v[234:237], v[46:49]
	v_mfma_f32_16x16x32_bf16 v[32:35], v[32:35], v[180:183], v[36:39]
	v_mfma_f32_16x16x32_bf16 v[28:31], v[28:31], v[246:249], v[32:35]
	s_nop 5
	v_sub_f32_e32 v40, v45, v40
	v_and_b32_e32 v45, 0xffff0000, v194
	v_sub_f32_e32 v41, v45, v41
	v_lshlrev_b32_e32 v45, 16, v195
	v_sub_f32_e32 v42, v45, v42
	v_and_b32_e32 v45, 0xffff0000, v195
	v_sub_f32_e32 v43, v45, v43
	v_cvt_pk_bf16_f32 v40, v40, v41
	v_cvt_pk_bf16_f32 v41, v42, v43
	v_or_b32_e32 v36, s64, v215
	ds_write_b64 v226, v[40:41] offset:8192
	s_waitcnt lgkmcnt(0)
	s_barrier
	v_mfma_f32_16x16x32_bf16 v[32:35], v[20:23], v[234:237], v[28:31]
	s_nop 2
	ds_read_b128 v[28:31], v36 offset:8192
	ds_read_b128 v[20:23], v36 offset:9216
	s_waitcnt lgkmcnt(1)
	v_mfma_f32_16x16x32_bf16 v[180:183], v[24:27], v[28:31], v[32:35]
	s_and_saveexec_b64 s[8:9], vcc
	s_xor_b64 s[8:9], exec, s[8:9]
	s_andn2_saveexec_b64 s[8:9], s[8:9]
	s_cbranch_execz .LBB0_878
	s_waitcnt lgkmcnt(0)
	v_mfma_f32_16x16x32_bf16 v[180:183], v[16:19], v[20:23], v[180:183]
.LBB0_878:
	s_or_b64 exec, exec, s[8:9]
	v_pk_mul_f32 v[18:19], v[170:171], v[240:241] op_sel_hi:[1,0]
	v_pk_mul_f32 v[16:17], v[168:169], v[240:241] op_sel_hi:[1,0]
	s_lshl_b32 s0, s0, 2
	s_xor_b32 s0, s0, 4
	v_mfma_f32_16x16x32_bf16 v[12:15], v[12:15], v[28:31], v[16:19]
	v_add_lshl_u32 v225, s0, v218, 10
	v_lshl_add_u64 v[210:211], s[16:17], 0, v[196:197]
	s_waitcnt lgkmcnt(0)
	v_mfma_f32_16x16x32_bf16 v[176:179], v[8:11], v[20:23], v[12:15]
	v_mul_f32_e64 v10, v174, v240
	v_mul_f32_e64 v11, v175, v240
	v_pk_mul_f32 v[8:9], v[172:173], v[240:241] op_sel_hi:[1,0]
	v_lshl_add_u64 v[172:173], s[54:55], 0, v[204:205]
	v_cvt_pk_bf16_f32 v174, v180, s0
	v_mfma_f32_16x16x32_bf16 v[4:7], v[4:7], v[28:31], v[8:11]
	v_mfma_f32_16x16x32_bf16 v[168:171], v[0:3], v[20:23], v[4:7]
	s_nop 1
	v_cvt_pk_bf16_f32 v8, v176, v177
	v_cvt_pk_bf16_f32 v9, v178, v179
	v_or_b32_e32 v0, v215, v225
	s_nop 2
	v_cvt_pk_bf16_f32 v10, v168, v169
	v_cvt_pk_bf16_f32 v11, v170, v171
	ds_write_b128 v0, v[8:11]
	v_lshl_add_u64 v[0:1], s[46:47], 0, v[184:185]
	v_add_co_u32_e64 v2, s[8:9], s56, v0
	s_nop 1
	v_addc_co_u32_e64 v3, s[8:9], 0, v1, s[8:9]
	global_load_dwordx4 v[52:55], v[2:3], off
	global_load_dwordx4 v[48:51], v[2:3], off offset:1024
	global_load_dwordx4 v[44:47], v[2:3], off offset:2048
	global_load_dwordx4 v[40:43], v[2:3], off offset:3072
	v_add_co_u32_e64 v2, s[8:9], s57, v0
	s_nop 1
	v_addc_co_u32_e64 v3, s[8:9], 0, v1, s[8:9]
	global_load_dwordx4 v[36:39], v[2:3], off
	global_load_dwordx4 v[32:35], v[2:3], off offset:1024
	global_load_dwordx4 v[28:31], v[2:3], off offset:2048
	global_load_dwordx4 v[20:23], v[2:3], off offset:3072
	v_lshl_add_u64 v[2:3], s[46:47], 0, v[188:189]
	v_add_co_u32_e64 v2, s[8:9], s56, v2
	s_nop 1
	v_addc_co_u32_e64 v3, s[8:9], 0, v3, s[8:9]
	v_add_co_u32_e64 v0, s[8:9], s58, v0
	global_load_dwordx4 v[24:27], v[2:3], off
	global_load_dwordx4 v[16:19], v[2:3], off offset:1024
	v_addc_co_u32_e64 v1, s[8:9], 0, v1, s[8:9]
	global_load_dwordx4 v[12:15], v[0:1], off
	global_load_dwordx4 v[8:11], v[0:1], off offset:1024
	global_load_dwordx4 v[4:7], v[0:1], off offset:2048
	s_nop 0
	global_load_dwordx4 v[0:3], v[0:1], off offset:3072
	s_nop 0
	global_load_dwordx2 v[194:195], v[172:173], off
	global_load_dword v240, v224, s[98:99] offset:12
	v_lshl_add_u64 v[172:173], v[202:203], 0, v[200:201]
	global_store_short v[172:173], v174, off
	v_or_b32_e32 v172, 0x800, v210
	v_mov_b32_e32 v173, v211
	v_cvt_pk_bf16_f32 v174, v181, s0
	v_lshl_add_u64 v[172:173], v[190:191], 0, v[172:173]
	global_store_short v[172:173], v174, off
	v_or_b32_e32 v172, 0x1000, v210
	v_mov_b32_e32 v173, v211
	v_cvt_pk_bf16_f32 v174, v182, s0
	v_lshl_add_u64 v[172:173], v[190:191], 0, v[172:173]
	global_store_short v[172:173], v174, off
	v_cvt_pk_bf16_f32 v174, v183, s0
	s_add_i32 s0, s61, 4
	v_or_b32_e32 v172, 0x1800, v210
	v_mov_b32_e32 v173, v211
	s_and_b32 s66, s0, 1
	v_lshl_add_u64 v[172:173], v[190:191], 0, v[172:173]
	v_lshl_or_b32 v212, s66, 12, v215
	global_store_short v[172:173], v174, off
	s_waitcnt lgkmcnt(0)
	s_barrier
	s_waitcnt vmcnt(40)
	ds_read_b128 v[172:175], v212
	ds_read_b128 v[180:183], v212 offset:1024
	ds_read_b128 v[246:249], v212 offset:2048
	ds_read_b128 v[230:233], v212 offset:3072
	s_waitcnt lgkmcnt(3)
	v_mfma_f32_16x16x32_bf16 v[112:115], v[112:115], v[172:175], 0
	s_lshl_b32 s8, s66, 11
	s_waitcnt lgkmcnt(2)
	v_mfma_f32_16x16x32_bf16 v[112:115], v[116:119], v[180:183], v[112:115]
	s_waitcnt lgkmcnt(1)
	v_mfma_f32_16x16x32_bf16 v[110:113], v[108:111], v[246:249], v[112:115]
	v_mfma_f32_16x16x32_bf16 v[100:103], v[100:103], v[172:175], 0
	s_waitcnt lgkmcnt(0)
	v_mfma_f32_16x16x32_bf16 v[104:107], v[104:107], v[230:233], v[110:113]
	v_mfma_f32_16x16x32_bf16 v[88:91], v[88:91], v[180:183], v[100:103]
	s_nop 2
	v_lshlrev_b32_e32 v110, 16, v206
	v_and_b32_e32 v111, 0xffff0000, v206
	s_nop 1
	v_pk_add_f32 v[104:105], v[110:111], v[104:105] neg_lo:[0,1] neg_hi:[0,1]
	v_lshlrev_b32_e32 v110, 16, v207
	v_and_b32_e32 v111, 0xffff0000, v207
	v_mfma_f32_16x16x32_bf16 v[80:83], v[80:83], v[246:249], v[88:91]
	v_add_f32_e64 v106, v110, -v106
	v_add_f32_e64 v107, v111, -v107
	v_cvt_pk_bf16_f32 v104, v104, v105
	v_cvt_pk_bf16_f32 v105, v106, v107
	v_add_u32_e32 v100, s8, v223
	ds_write_b64 v100, v[104:105] offset:8192
	v_or_b32_e32 v100, s8, v215
	s_waitcnt lgkmcnt(0)
	s_barrier
	v_mfma_f32_16x16x32_bf16 v[88:91], v[76:79], v[230:233], v[80:83]
	s_nop 2
	ds_read_b128 v[80:83], v100 offset:8192
	ds_read_b128 v[76:79], v100 offset:9216
	s_waitcnt lgkmcnt(1)
	v_mfma_f32_16x16x32_bf16 v[180:183], v[84:87], v[80:83], v[88:91]
	s_and_saveexec_b64 s[8:9], s[6:7]
	s_cbranch_execz .LBB0_880
	s_waitcnt lgkmcnt(0)
	v_mfma_f32_16x16x32_bf16 v[180:183], v[72:75], v[76:79], v[180:183]
; __device__ __forceinline__ u16 f2bf(float f) { return (u16)(pack2(f, f) & 0xffffu); }
; __device__ __forceinline__ float lo_bf(unsigned u) { return __uint_as_float(u << 16); }
; __device__ __forceinline__ float hi_bf(unsigned u) { return __uint_as_float(u & 0xffff0000u); }
; #define MFMA16(a, b, c) __builtin_amdgcn_mfma_f32_16x16x32_bf16(a, b, c, 0, 0, 0)
; __device__ __forceinline__ void scan_block(const Params& p, char* smem, int bs) {
;     ...
;   auto step = [&](const int ch, u32x4 (&F)[14], uint2& U) {
;     const int par = ch & 1;
;     const float cd = cdp[ch];
;     union { u32x4 u; bf16x8 v; } cv;
;     f32x4 aw = {0.f, 0.f, 0.f, 0.f}, aq = aw;
; #pragma unroll
;     for (int s2 = 0; s2 < 4; ++s2) {
;       union { u32x4 u; bf16x8 v; } sb;
;       sb.u = *(const u32x4*)(Sl + ((par * 4 + s2) * 64 + lane) * 16);
;       cv.u = F[s2];     aw = MFMA16(cv.v, sb.v, aw);
;       cv.u = F[4 + s2]; aq = MFMA16(cv.v, sb.v, aq);
;     }
;     f32x4 vn;
;     vn[0] = lo_bf(U.x) - aw[0]; vn[1] = hi_bf(U.x) - aw[1];
;     vn[2] = lo_bf(U.y) - aw[2]; vn[3] = hi_bf(U.y) - aw[3];
;     {
;       uint2 pk; pk.x = pack2(vn[0], vn[1]); pk.y = pack2(vn[2], vn[3]);
;       *(uint2*)(Vl + ((par * 2 + (w >> 1)) * 64 + lane) * 16 + (w & 1) * 8) = pk;
;     }
;     __syncthreads();
;     bf16x8 Vb[2];
; #pragma unroll
;     for (int m = 0; m < 2; ++m) { cv.u = *(const u32x4*)(Vl + ((par * 2 + m) * 64 + lane) * 16); Vb[m] = cv.v; }
;     cv.u = F[8]; aq = MFMA16(cv.v, Vb[0], aq);
;     if (w >= 2) { cv.u = F[9]; aq = MFMA16(cv.v, Vb[1], aq); }
;     f32x4 n0 = S0 * cd, n1 = S1 * cd;
;     cv.u = F[10]; n0 = MFMA16(cv.v, Vb[0], n0);
;     cv.u = F[11]; n0 = MFMA16(cv.v, Vb[1], n0);
;     cv.u = F[12]; n1 = MFMA16(cv.v, Vb[0], n1);
;     cv.u = F[13]; n1 = MFMA16(cv.v, Vb[1], n1);
;     S0 = n0; S1 = n1;
;     {
;       cv.v = pack8(S0, S1);
;       *(u32x4*)(Sl + (((par ^ 1) * 4 + w) * 64 + lane) * 16) = cv.u;
;     }
;     {
;       const int nx = (ch + 3 < 256) ? ch + 3 : 255;
;       LOADSET(F, U, nx);
;     }
; #pragma unroll
;     for (int jj = 0; jj < 4; ++jj) {
;       const size_t row = (size_t)b * T + ch * 64 + w * 16 + 4 * fq + jj;
;       oraw[row * 1024 + hh * 128 + slice * 16 + fr] = f2bf(aq[jj]);
;     }
;     __syncthreads();
;   };
.LBB0_880:
	s_or_b64 exec, exec, s[8:9]
	v_pk_mul_f32 v[74:75], v[178:179], v[242:243] op_sel_hi:[1,0]
	v_pk_mul_f32 v[72:73], v[176:177], v[242:243] op_sel_hi:[1,0]
	s_min_u32 s0, s0, 0xfc
	s_lshl_b32 s8, s66, 2
	v_mfma_f32_16x16x32_bf16 v[68:71], v[68:71], v[80:83], v[72:75]
	s_add_i32 s0, s0, 3
	v_lshl_add_u64 v[212:213], s[54:55], 0, v[198:199]
	v_add_u32_e32 v227, s65, v215
	s_waitcnt lgkmcnt(0)
	v_mfma_f32_16x16x32_bf16 v[172:175], v[64:67], v[76:79], v[68:71]
	v_mul_f32_e64 v66, v170, v242
	v_mul_f32_e64 v67, v171, v242
	v_pk_mul_f32 v[64:65], v[168:169], v[242:243] op_sel_hi:[1,0]
	s_nop 1
	v_mfma_f32_16x16x32_bf16 v[60:63], v[60:63], v[80:83], v[64:67]
	v_mfma_f32_16x16x32_bf16 v[168:171], v[56:59], v[76:79], v[60:63]
	v_xad_u32 v56, s8, 4, v218
	s_mul_i32 s8, s0, 0xe000
	s_add_u32 s66, s10, s8
	v_cvt_pk_bf16_f32 v64, v172, v173
	v_cvt_pk_bf16_f32 v65, v174, v175
	s_nop 2
	v_cvt_pk_bf16_f32 v66, v168, v169
	v_cvt_pk_bf16_f32 v67, v170, v171
	v_lshl_or_b32 v56, v56, 10, v215
	s_addc_u32 s67, s11, 0
	ds_write_b128 v56, v[64:67]
	v_lshl_add_u64 v[56:57], s[66:67], 0, v[184:185]
	v_lshl_add_u64 v[58:59], v[56:57], 0, s[12:13]
	v_add_co_u32_e64 v60, s[8:9], s50, v56
	global_load_dwordx4 v[112:115], v[56:57], off
	global_load_dwordx4 v[116:119], v[56:57], off offset:1024
	global_load_dwordx4 v[108:111], v[56:57], off offset:2048
	global_load_dwordx4 v[104:107], v[56:57], off offset:3072
	v_addc_co_u32_e64 v61, s[8:9], 0, v57, s[8:9]
	global_load_dwordx4 v[88:91], v[58:59], off offset:1024
	global_load_dwordx4 v[80:83], v[58:59], off offset:2048
	global_load_dwordx4 v[100:103], v[60:61], off
	global_load_dwordx4 v[76:79], v[58:59], off offset:3072
	v_lshl_add_u64 v[58:59], s[66:67], 0, v[188:189]
	global_load_dwordx4 v[84:87], v[58:59], off
	global_load_dwordx4 v[72:75], v[58:59], off offset:1024
	v_lshl_add_u64 v[58:59], v[56:57], 0, s[14:15]
	v_add_co_u32_e64 v56, s[8:9], s51, v56
	s_lshl_b32 s0, s0, 14
	s_nop 0
	v_addc_co_u32_e64 v57, s[8:9], 0, v57, s[8:9]
	v_lshl_add_u64 v[176:177], v[192:193], 0, s[0:1]
	v_add_co_u32_e64 v178, s[8:9], s59, v212
	global_load_dwordx4 v[64:67], v[58:59], off offset:1024
	global_load_dwordx4 v[60:63], v[58:59], off offset:2048
	global_load_dwordx4 v[68:71], v[56:57], off
	s_nop 0
	global_load_dwordx4 v[56:59], v[58:59], off offset:3072
	v_cvt_pk_bf16_f32 v180, v180, s0
	global_load_dwordx2 v[206:207], v[176:177], off
	global_load_dword v242, v224, s[98:99] offset:16
	v_lshl_add_u64 v[176:177], v[210:211], 0, s[20:21]
	v_addc_co_u32_e64 v179, s[8:9], 0, v213, s[8:9]
	global_store_short v[178:179], v180, off
	v_or_b32_e32 v178, 0x800, v176
	v_mov_b32_e32 v179, v177
	v_cvt_pk_bf16_f32 v180, v181, s0
	v_lshl_add_u64 v[178:179], v[190:191], 0, v[178:179]
	global_store_short v[178:179], v180, off
	v_or_b32_e32 v178, 0x1000, v176
	v_mov_b32_e32 v179, v177
	v_cvt_pk_bf16_f32 v180, v182, s0
	v_lshl_add_u64 v[178:179], v[190:191], 0, v[178:179]
	v_or_b32_e32 v176, 0x1800, v176
	global_store_short v[178:179], v180, off
	v_cvt_pk_bf16_f32 v178, v183, s0
	v_lshl_add_u64 v[176:177], v[190:191], 0, v[176:177]
	global_store_short v[176:177], v178, off
	s_waitcnt lgkmcnt(0)
	s_barrier
	s_waitcnt vmcnt(40)
	ds_read_b128 v[176:179], v227
	ds_read_b128 v[180:183], v227 offset:1024
	ds_read_b128 v[246:249], v227 offset:2048
	ds_read_b128 v[230:233], v227 offset:3072
	s_waitcnt lgkmcnt(3)
	v_mfma_f32_16x16x32_bf16 v[160:163], v[160:163], v[176:179], 0
	s_waitcnt lgkmcnt(2)
	v_mfma_f32_16x16x32_bf16 v[160:163], v[164:167], v[180:183], v[160:163]
	s_waitcnt lgkmcnt(1)
	v_mfma_f32_16x16x32_bf16 v[158:161], v[156:159], v[246:249], v[160:163]
	v_mfma_f32_16x16x32_bf16 v[148:151], v[148:151], v[176:179], 0
	v_mfma_f32_16x16x32_bf16 v[144:147], v[144:147], v[180:183], v[148:151]
	s_waitcnt lgkmcnt(0)
	v_mfma_f32_16x16x32_bf16 v[152:155], v[152:155], v[230:233], v[158:161]
	s_nop 4
	v_add_u32_e32 v148, s64, v215
	v_lshlrev_b32_e32 v158, 16, v208
	v_and_b32_e32 v159, 0xffff0000, v208
	v_mfma_f32_16x16x32_bf16 v[136:139], v[136:139], v[246:249], v[144:147]
	v_add_f32_e64 v152, v158, -v152
	v_add_f32_e64 v153, v159, -v153
	v_lshlrev_b32_e32 v158, 16, v209
	v_and_b32_e32 v159, 0xffff0000, v209
	v_pk_add_f32 v[154:155], v[158:159], v[154:155] neg_lo:[0,1] neg_hi:[0,1]
	v_cvt_pk_bf16_f32 v152, v152, v153
	v_cvt_pk_bf16_f32 v153, v154, v155
	ds_write_b64 v226, v[152:153] offset:8192
	s_waitcnt lgkmcnt(0)
	s_barrier
	v_mfma_f32_16x16x32_bf16 v[144:147], v[132:135], v[230:233], v[136:139]
	s_nop 2
	ds_read_b128 v[136:139], v148 offset:8192
	ds_read_b128 v[132:135], v148 offset:9216
	s_waitcnt lgkmcnt(1)
	v_mfma_f32_16x16x32_bf16 v[176:179], v[140:143], v[136:139], v[144:147]
	s_and_saveexec_b64 s[8:9], s[6:7]
	s_cbranch_execz .LBB0_882
	s_waitcnt lgkmcnt(0)
	v_mfma_f32_16x16x32_bf16 v[176:179], v[128:131], v[132:135], v[176:179]
